# v063 plus multi-unit GEMM phases (P1, P8, P14): first K-loop iteration of every unit peeled with SrcC = 0 on each accumulator's first MFMA, the 128 accumulator-zeroing v_mov per unit removed
# speedup vs baseline: 1.0069x; 1.0069x over previous
; #define PG8_STAGE(bufoff, gbase, voff) do { _Pragma("unroll") for (int _i = 0; _i < 2; ++_i) \
;         __builtin_amdgcn_global_load_lds((const unsigned*)((const char*)(gbase) + (voff)[_i]), (PG8_LAS unsigned*)(lds + (bufoff) + ldsw + _i * 8192), 16, 0, 0); } while (0)
; #define PG8_LDA(dst, b, h) do { _Pragma("unroll") for (int m = 0; m < 4; ++m) _Pragma("unroll") for (int k = 0; k < 2; ++k) dst[m][k] = *(const PG8_LAS bf16x8*)(lds + PG8_SA(b, h) + aoff + m * 2048 + k * 1024); } while (0)
; #define PG8_LDB(dst, b, h) do { _Pragma("unroll") for (int n = 0; n < 2; ++n) _Pragma("unroll") for (int k = 0; k < 2; ++k) dst[n][k] = *(const PG8_LAS bf16x8*)(lds + PG8_SB(b, h) + boff + n * 2048 + k * 1024); } while (0)
; #define PG8_WAIT_V(n) asm volatile("s_waitcnt vmcnt(" #n ")" ::: "memory")
; #define PG8_WAIT_L(n) asm volatile("s_waitcnt lgkmcnt(" #n ")" ::: "memory")
; #define PG8_BAR __builtin_amdgcn_s_barrier()
; #define PG8_SCHED __builtin_amdgcn_sched_barrier(0)
; template <class Epi, class Sched, bool ALIGN_EPI = false, bool SP2 = false>
; __device__ __forceinline__ void gemm_phase(PG8_LAS unsigned char* lds, const Gemm g, const Sched& S, const Epi& E) {
;     ...
;         const bool has_next = S.next(ui + 1, nxt);
;         const char* nA = has_next ? PG8_UA(nxt) : cA; const char* nB = has_next ? PG8_UB(nxt) : cB;
;         for (int t = 0; t < nt; t += 2) {
;             const bool last = (t == nt - 2);
;             const char* a1 = cA + (size_t)(t + 1) * kstep;
;             const char* a2 = last ? nA : cA + (size_t)(t + 2) * kstep; const char* b2 = last ? nB : cB + (size_t)(t + 2) * kstep;
;             const char* a3 = a2 + kstep; const char* b3 = b2 + kstep;
;             if (last && has_next) S.a_ready(nxt);
;             if constexpr (SP2) {
;             PG8_LDB(B0, 0, 0); PG8_LDB(B1, 0, 1); PG8_SCHED; PG8_LDA(At, 0, 0); PG8_STAGE(PG8_SA(1, 1), a1 + hstepA, voffA);
;             PG8_WAIT_V(8); PG8_WAIT_L(0); PG8_BAR; PG8_MMA(0, 0, At, B0); PG8_MMA(0, 1, At, B1); PG8_BAR; PG8_SCHED;
;             PG8_LDA(At, 0, 1); PG8_STAGE(PG8_SB(0, 0), b2, voffB); PG8_STAGE(PG8_SB(0, 1), b2 + hstepB, voffB); PG8_STAGE(PG8_SA(0, 0), a2, voffA);
;             PG8_WAIT_V(8); PG8_WAIT_L(0); PG8_BAR; PG8_MMA(1, 0, At, B0); PG8_MMA(1, 1, At, B1); PG8_BAR; PG8_SCHED;
.LBB0_294:
	s_ashr_i32 s17, s16, 31
	s_lshl_b64 s[2:3], s[16:17], 19
	v_readlane_b32 s18, v251, 39
	v_readlane_b32 s19, v251, 40
	s_add_u32 s18, s18, s2
	s_addc_u32 s19, s19, s3
	s_and_b64 s[2:3], s[4:5], exec
	s_cselect_b32 s2, s19, s25
	s_cselect_b32 s3, s18, s24
	s_ashr_i32 s17, s16, 30
	s_add_i32 s20, s17, s80
	s_ashr_i32 s21, s20, 31
	s_lshl_b64 s[20:21], s[20:21], 19
	s_add_u32 s20, s42, s20
	s_addc_u32 s21, s43, s21
	s_and_b64 s[28:29], s[4:5], exec
	s_cselect_b32 s17, s21, s27
	s_cselect_b32 s23, s20, s26
	s_add_u32 s24, s24, 0x40080
	s_addc_u32 s25, s25, 0
	s_add_u32 s82, s26, 0x100
	s_addc_u32 s83, s27, 0
	s_mov_b32 s84, -2
	ds_read_b128 v[128:131], v219
	ds_read_b128 v[132:135], v219 offset:1024
	ds_read_b128 v[136:139], v219 offset:2048
	ds_read_b128 v[140:143], v219 offset:3072
	ds_read_b128 v[144:147], v220
	ds_read_b128 v[148:151], v220 offset:1024
	ds_read_b128 v[152:155], v220 offset:2048
	ds_read_b128 v[156:159], v220 offset:3072
	s_add_u32 s26, s24, 0xfffc0080
	s_addc_u32 s27, s25, -1
	s_cmp_eq_u32 s84, 12
	s_cselect_b32 s29, s2, s27
	s_cselect_b32 s28, s3, s26
	s_cselect_b32 s27, s17, s83
	s_cselect_b32 s26, s23, s82
	v_lshl_add_u64 v[224:225], s[24:25], 0, v[208:209]
	s_add_i32 m0, s53, 0xc000
	ds_read_b128 v[160:163], v221
	ds_read_b128 v[164:167], v221 offset:1024
	ds_read_b128 v[168:171], v221 offset:2048
	ds_read_b128 v[172:175], v221 offset:3072
	ds_read_b128 v[176:179], v221 offset:4096
	ds_read_b128 v[180:183], v221 offset:5120
	ds_read_b128 v[184:187], v221 offset:6144
	ds_read_b128 v[188:191], v221 offset:7168
	global_load_lds_dwordx4 v[224:225], off
	v_lshl_add_u64 v[224:225], s[24:25], 0, v[210:211]
	s_add_i32 m0, s53, 0xe000
	s_nop 0
	global_load_lds_dwordx4 v[224:225], off
	s_waitcnt vmcnt(8)
	s_waitcnt lgkmcnt(0)
	s_barrier
	s_setprio 1
	s_waitcnt lgkmcnt(0)
	v_mfma_f32_16x16x32_bf16 v[124:127], v[128:131], v[160:163], 0
	v_mfma_f32_16x16x32_bf16 v[120:123], v[136:139], v[160:163], 0
	v_mfma_f32_16x16x32_bf16 v[116:119], v[128:131], v[168:171], 0
	v_mfma_f32_16x16x32_bf16 v[108:111], v[136:139], v[168:171], 0
	v_mfma_f32_16x16x32_bf16 v[100:103], v[128:131], v[176:179], 0
	v_mfma_f32_16x16x32_bf16 v[92:95], v[136:139], v[176:179], 0
	v_mfma_f32_16x16x32_bf16 v[84:87], v[128:131], v[184:187], 0
	v_mfma_f32_16x16x32_bf16 v[76:79], v[136:139], v[184:187], 0
	v_mfma_f32_16x16x32_bf16 v[124:127], v[132:135], v[164:167], v[124:127]
	v_mfma_f32_16x16x32_bf16 v[120:123], v[140:143], v[164:167], v[120:123]
	v_mfma_f32_16x16x32_bf16 v[116:119], v[132:135], v[172:175], v[116:119]
	v_mfma_f32_16x16x32_bf16 v[108:111], v[140:143], v[172:175], v[108:111]
	v_mfma_f32_16x16x32_bf16 v[100:103], v[132:135], v[180:183], v[100:103]
	v_mfma_f32_16x16x32_bf16 v[92:95], v[140:143], v[180:183], v[92:95]
	v_mfma_f32_16x16x32_bf16 v[84:87], v[132:135], v[188:191], v[84:87]
	v_mfma_f32_16x16x32_bf16 v[76:79], v[140:143], v[188:191], v[76:79]
	s_setprio 0
	s_setprio 1
	v_mfma_f32_16x16x32_bf16 v[112:115], v[144:147], v[160:163], 0
	v_mfma_f32_16x16x32_bf16 v[104:107], v[152:155], v[160:163], 0
	v_mfma_f32_16x16x32_bf16 v[96:99], v[144:147], v[168:171], 0
	v_mfma_f32_16x16x32_bf16 v[88:91], v[152:155], v[168:171], 0
	v_mfma_f32_16x16x32_bf16 v[80:83], v[144:147], v[176:179], 0
	v_mfma_f32_16x16x32_bf16 v[72:75], v[152:155], v[176:179], 0
	v_mfma_f32_16x16x32_bf16 v[68:71], v[144:147], v[184:187], 0
	v_mfma_f32_16x16x32_bf16 v[64:67], v[152:155], v[184:187], 0
	v_mfma_f32_16x16x32_bf16 v[112:115], v[148:151], v[164:167], v[112:115]
	v_mfma_f32_16x16x32_bf16 v[104:107], v[156:159], v[164:167], v[104:107]
	v_mfma_f32_16x16x32_bf16 v[96:99], v[148:151], v[172:175], v[96:99]
	v_mfma_f32_16x16x32_bf16 v[88:91], v[156:159], v[172:175], v[88:91]
	v_mfma_f32_16x16x32_bf16 v[80:83], v[148:151], v[180:183], v[80:83]
	v_mfma_f32_16x16x32_bf16 v[72:75], v[156:159], v[180:183], v[72:75]
	v_mfma_f32_16x16x32_bf16 v[68:71], v[148:151], v[188:191], v[68:71]
	v_mfma_f32_16x16x32_bf16 v[64:67], v[156:159], v[188:191], v[64:67]
	s_setprio 0
	s_barrier
	s_add_i32 s85, s73, s44
	v_lshl_add_u64 v[224:225], s[26:27], 0, v[200:201]
	s_mov_b32 m0, s85
	ds_read_b128 v[160:163], v221 offset:16384
	ds_read_b128 v[164:167], v221 offset:17408
	ds_read_b128 v[168:171], v221 offset:18432
	ds_read_b128 v[172:175], v221 offset:19456
	ds_read_b128 v[176:179], v221 offset:20480
	ds_read_b128 v[180:183], v221 offset:21504
	ds_read_b128 v[184:187], v221 offset:22528
	ds_read_b128 v[188:191], v221 offset:23552
	global_load_lds_dwordx4 v[224:225], off
	s_add_i32 m0, s85, 0x2000
	s_add_u32 s86, s26, 0x40000
	v_lshl_add_u64 v[226:227], s[26:27], 0, v[196:197]
	s_addc_u32 s87, s27, 0
	s_add_i32 s85, s74, s44
	global_load_lds_dwordx4 v[226:227], off
	v_lshl_add_u64 v[228:229], s[86:87], 0, v[200:201]
	s_mov_b32 m0, s85
	v_lshl_add_u64 v[230:231], s[28:29], 0, v[198:199]
	global_load_lds_dwordx4 v[228:229], off
	v_lshl_add_u64 v[228:229], s[86:87], 0, v[196:197]
	s_add_i32 m0, s85, 0x2000
	s_nop 0
	global_load_lds_dwordx4 v[228:229], off
	v_lshl_add_u64 v[228:229], s[28:29], 0, v[202:203]
	s_mov_b32 m0, s53
	s_nop 0
	global_load_lds_dwordx4 v[228:229], off
	s_mov_b32 m0, s54
	s_nop 0
	global_load_lds_dwordx4 v[230:231], off
	s_waitcnt vmcnt(8)
	s_waitcnt lgkmcnt(0)
	s_barrier
; #define PG8_STAGE(bufoff, gbase, voff) do { _Pragma("unroll") for (int _i = 0; _i < 2; ++_i) \
;         __builtin_amdgcn_global_load_lds((const unsigned*)((const char*)(gbase) + (voff)[_i]), (PG8_LAS unsigned*)(lds + (bufoff) + ldsw + _i * 8192), 16, 0, 0); } while (0)
; #define PG8_LDA(dst, b, h) do { _Pragma("unroll") for (int m = 0; m < 4; ++m) _Pragma("unroll") for (int k = 0; k < 2; ++k) dst[m][k] = *(const PG8_LAS bf16x8*)(lds + PG8_SA(b, h) + aoff + m * 2048 + k * 1024); } while (0)
; #define PG8_LDB(dst, b, h) do { _Pragma("unroll") for (int n = 0; n < 2; ++n) _Pragma("unroll") for (int k = 0; k < 2; ++k) dst[n][k] = *(const PG8_LAS bf16x8*)(lds + PG8_SB(b, h) + boff + n * 2048 + k * 1024); } while (0)
; #define PG8_MMA(ai, bj, At, Bt) do { __builtin_amdgcn_s_setprio(1); _Pragma("unroll") for (int m = 0; m < 4; ++m) _Pragma("unroll") for (int n = 0; n < 2; ++n) _Pragma("unroll") for (int k = 0; k < 2; ++k) \
;         acc[ai][bj][m][n] = __builtin_amdgcn_mfma_f32_16x16x32_bf16(Bt[n][k], At[m][k], acc[ai][bj][m][n], 0, 0, 0); __builtin_amdgcn_s_setprio(0); } while (0)
; #define PG8_WAIT_V(n) asm volatile("s_waitcnt vmcnt(" #n ")" ::: "memory")
; #define PG8_WAIT_L(n) asm volatile("s_waitcnt lgkmcnt(" #n ")" ::: "memory")
; #define PG8_BAR __builtin_amdgcn_s_barrier()
; #define PG8_SCHED __builtin_amdgcn_sched_barrier(0)
; template <class Epi, class Sched, bool ALIGN_EPI = false, bool SP2 = false>
; __device__ __forceinline__ void gemm_phase(PG8_LAS unsigned char* lds, const Gemm g, const Sched& S, const Epi& E) {
;     ...
;             PG8_WAIT_V(8); PG8_WAIT_L(0); PG8_BAR; PG8_MMA(1, 0, At, B0); PG8_MMA(1, 1, At, B1); PG8_BAR; PG8_SCHED;
;             PG8_LDB(B0, 1, 0); PG8_LDB(B1, 1, 1); PG8_SCHED; PG8_LDA(At, 1, 0); PG8_STAGE(PG8_SA(0, 1), a2 + hstepA, voffA);
;             PG8_WAIT_V(8); PG8_WAIT_L(0); PG8_BAR; PG8_MMA(0, 0, At, B0); PG8_MMA(0, 1, At, B1); PG8_BAR; PG8_SCHED;
	s_setprio 1
	s_waitcnt lgkmcnt(0)
	v_mfma_f32_16x16x32_bf16 v[60:63], v[128:131], v[160:163], 0
	v_mfma_f32_16x16x32_bf16 v[56:59], v[136:139], v[160:163], 0
	v_mfma_f32_16x16x32_bf16 v[52:55], v[128:131], v[168:171], 0
	v_mfma_f32_16x16x32_bf16 v[44:47], v[136:139], v[168:171], 0
	v_mfma_f32_16x16x32_bf16 v[36:39], v[128:131], v[176:179], 0
	v_mfma_f32_16x16x32_bf16 v[28:31], v[136:139], v[176:179], 0
	v_mfma_f32_16x16x32_bf16 v[20:23], v[128:131], v[184:187], 0
	v_mfma_f32_16x16x32_bf16 v[12:15], v[136:139], v[184:187], 0
	v_mfma_f32_16x16x32_bf16 v[60:63], v[132:135], v[164:167], v[60:63]
	v_mfma_f32_16x16x32_bf16 v[56:59], v[140:143], v[164:167], v[56:59]
	v_mfma_f32_16x16x32_bf16 v[52:55], v[132:135], v[172:175], v[52:55]
	v_mfma_f32_16x16x32_bf16 v[44:47], v[140:143], v[172:175], v[44:47]
	v_mfma_f32_16x16x32_bf16 v[36:39], v[132:135], v[180:183], v[36:39]
	v_mfma_f32_16x16x32_bf16 v[28:31], v[140:143], v[180:183], v[28:31]
	v_mfma_f32_16x16x32_bf16 v[20:23], v[132:135], v[188:191], v[20:23]
	v_mfma_f32_16x16x32_bf16 v[12:15], v[140:143], v[188:191], v[12:15]
	s_setprio 0
	s_setprio 1
	v_mfma_f32_16x16x32_bf16 v[48:51], v[144:147], v[160:163], 0
	v_mfma_f32_16x16x32_bf16 v[40:43], v[152:155], v[160:163], 0
	v_mfma_f32_16x16x32_bf16 v[32:35], v[144:147], v[168:171], 0
	v_mfma_f32_16x16x32_bf16 v[24:27], v[152:155], v[168:171], 0
	v_mfma_f32_16x16x32_bf16 v[16:19], v[144:147], v[176:179], 0
	v_mfma_f32_16x16x32_bf16 v[8:11], v[152:155], v[176:179], 0
	v_mfma_f32_16x16x32_bf16 v[4:7], v[144:147], v[184:187], 0
	v_mfma_f32_16x16x32_bf16 v[0:3], v[152:155], v[184:187], 0
	v_mfma_f32_16x16x32_bf16 v[48:51], v[148:151], v[164:167], v[48:51]
	v_mfma_f32_16x16x32_bf16 v[40:43], v[156:159], v[164:167], v[40:43]
	v_mfma_f32_16x16x32_bf16 v[32:35], v[148:151], v[172:175], v[32:35]
	v_mfma_f32_16x16x32_bf16 v[24:27], v[156:159], v[172:175], v[24:27]
	v_mfma_f32_16x16x32_bf16 v[16:19], v[148:151], v[180:183], v[16:19]
	v_mfma_f32_16x16x32_bf16 v[8:11], v[156:159], v[180:183], v[8:11]
	v_mfma_f32_16x16x32_bf16 v[4:7], v[148:151], v[188:191], v[4:7]
	v_mfma_f32_16x16x32_bf16 v[0:3], v[156:159], v[188:191], v[0:3]
	s_setprio 0
	s_barrier
	s_add_i32 s85, 0, 0x18000
	s_add_i32 s86, 0, 0x1c000
	v_add_u32_e32 v140, s85, v207
	v_add_u32_e32 v156, s86, v207
	ds_read_b128 v[128:131], v140
	ds_read_b128 v[132:135], v140 offset:1024
	ds_read_b128 v[136:139], v140 offset:2048
	ds_read_b128 v[140:143], v140 offset:3072
	ds_read_b128 v[144:147], v156
	ds_read_b128 v[148:151], v156 offset:1024
	ds_read_b128 v[152:155], v156 offset:2048
	ds_read_b128 v[156:159], v156 offset:3072
	s_add_u32 s28, s28, 0x40000
	s_addc_u32 s29, s29, 0
	s_mov_b32 m0, s55
	v_lshl_add_u64 v[232:233], s[28:29], 0, v[202:203]
	ds_read_b128 v[160:163], v221 offset:32768
	ds_read_b128 v[164:167], v221 offset:33792
	ds_read_b128 v[168:171], v221 offset:34816
	ds_read_b128 v[172:175], v221 offset:35840
	ds_read_b128 v[176:179], v221 offset:36864
	ds_read_b128 v[180:183], v221 offset:37888
	ds_read_b128 v[184:187], v221 offset:38912
	ds_read_b128 v[188:191], v221 offset:39936
	global_load_lds_dwordx4 v[232:233], off
	v_lshl_add_u64 v[232:233], s[28:29], 0, v[198:199]
	s_mov_b32 m0, s56
	s_nop 0
	global_load_lds_dwordx4 v[232:233], off
	s_waitcnt vmcnt(8)
	s_waitcnt lgkmcnt(0)
	s_barrier
	s_setprio 1
	s_waitcnt lgkmcnt(0)
	v_mfma_f32_16x16x32_bf16 v[124:127], v[128:131], v[160:163], v[124:127]
	v_mfma_f32_16x16x32_bf16 v[120:123], v[136:139], v[160:163], v[120:123]
	v_mfma_f32_16x16x32_bf16 v[116:119], v[128:131], v[168:171], v[116:119]
	v_mfma_f32_16x16x32_bf16 v[108:111], v[136:139], v[168:171], v[108:111]
	v_mfma_f32_16x16x32_bf16 v[100:103], v[128:131], v[176:179], v[100:103]
	v_mfma_f32_16x16x32_bf16 v[92:95], v[136:139], v[176:179], v[92:95]
	v_mfma_f32_16x16x32_bf16 v[84:87], v[128:131], v[184:187], v[84:87]
	v_mfma_f32_16x16x32_bf16 v[76:79], v[136:139], v[184:187], v[76:79]
	v_mfma_f32_16x16x32_bf16 v[124:127], v[132:135], v[164:167], v[124:127]
	v_mfma_f32_16x16x32_bf16 v[120:123], v[140:143], v[164:167], v[120:123]
	v_mfma_f32_16x16x32_bf16 v[116:119], v[132:135], v[172:175], v[116:119]
	v_mfma_f32_16x16x32_bf16 v[108:111], v[140:143], v[172:175], v[108:111]
	v_mfma_f32_16x16x32_bf16 v[100:103], v[132:135], v[180:183], v[100:103]
	v_mfma_f32_16x16x32_bf16 v[92:95], v[140:143], v[180:183], v[92:95]
	v_mfma_f32_16x16x32_bf16 v[84:87], v[132:135], v[188:191], v[84:87]
	v_mfma_f32_16x16x32_bf16 v[76:79], v[140:143], v[188:191], v[76:79]
	s_setprio 0
	s_setprio 1
	v_mfma_f32_16x16x32_bf16 v[112:115], v[144:147], v[160:163], v[112:115]
	v_mfma_f32_16x16x32_bf16 v[104:107], v[152:155], v[160:163], v[104:107]
	v_mfma_f32_16x16x32_bf16 v[96:99], v[144:147], v[168:171], v[96:99]
	v_mfma_f32_16x16x32_bf16 v[88:91], v[152:155], v[168:171], v[88:91]
	v_mfma_f32_16x16x32_bf16 v[80:83], v[144:147], v[176:179], v[80:83]
	v_mfma_f32_16x16x32_bf16 v[72:75], v[152:155], v[176:179], v[72:75]
	v_mfma_f32_16x16x32_bf16 v[68:71], v[144:147], v[184:187], v[68:71]
	v_mfma_f32_16x16x32_bf16 v[64:67], v[152:155], v[184:187], v[64:67]
	v_mfma_f32_16x16x32_bf16 v[112:115], v[148:151], v[164:167], v[112:115]
	v_mfma_f32_16x16x32_bf16 v[104:107], v[156:159], v[164:167], v[104:107]
	v_mfma_f32_16x16x32_bf16 v[96:99], v[148:151], v[172:175], v[96:99]
	v_mfma_f32_16x16x32_bf16 v[88:91], v[156:159], v[172:175], v[88:91]
	v_mfma_f32_16x16x32_bf16 v[80:83], v[148:151], v[180:183], v[80:83]
	v_mfma_f32_16x16x32_bf16 v[72:75], v[156:159], v[180:183], v[72:75]
	v_mfma_f32_16x16x32_bf16 v[68:71], v[148:151], v[188:191], v[68:71]
	v_mfma_f32_16x16x32_bf16 v[64:67], v[156:159], v[188:191], v[64:67]
	s_setprio 0
	s_barrier
; #define PG8_STAGE(bufoff, gbase, voff) do { _Pragma("unroll") for (int _i = 0; _i < 2; ++_i) \
;         __builtin_amdgcn_global_load_lds((const unsigned*)((const char*)(gbase) + (voff)[_i]), (PG8_LAS unsigned*)(lds + (bufoff) + ldsw + _i * 8192), 16, 0, 0); } while (0)
; #define PG8_LDA(dst, b, h) do { _Pragma("unroll") for (int m = 0; m < 4; ++m) _Pragma("unroll") for (int k = 0; k < 2; ++k) dst[m][k] = *(const PG8_LAS bf16x8*)(lds + PG8_SA(b, h) + aoff + m * 2048 + k * 1024); } while (0)
; #define PG8_MMA(ai, bj, At, Bt) do { __builtin_amdgcn_s_setprio(1); _Pragma("unroll") for (int m = 0; m < 4; ++m) _Pragma("unroll") for (int n = 0; n < 2; ++n) _Pragma("unroll") for (int k = 0; k < 2; ++k) \
;         acc[ai][bj][m][n] = __builtin_amdgcn_mfma_f32_16x16x32_bf16(Bt[n][k], At[m][k], acc[ai][bj][m][n], 0, 0, 0); __builtin_amdgcn_s_setprio(0); } while (0)
; #define PG8_WAIT_V(n) asm volatile("s_waitcnt vmcnt(" #n ")" ::: "memory")
; #define PG8_WAIT_L(n) asm volatile("s_waitcnt lgkmcnt(" #n ")" ::: "memory")
; #define PG8_BAR __builtin_amdgcn_s_barrier()
; #define PG8_SCHED __builtin_amdgcn_sched_barrier(0)
; template <class Epi, class Sched, bool ALIGN_EPI = false, bool SP2 = false>
; __device__ __forceinline__ void gemm_phase(PG8_LAS unsigned char* lds, const Gemm g, const Sched& S, const Epi& E) {
;     ...
;             PG8_LDA(At, 1, 1); PG8_STAGE(PG8_SB(1, 0), b3, voffB); PG8_STAGE(PG8_SB(1, 1), b3 + hstepB, voffB); PG8_STAGE(PG8_SA(1, 0), a3, voffA);
;             PG8_WAIT_V(8); PG8_WAIT_L(0); PG8_BAR; PG8_MMA(1, 0, At, B0); PG8_MMA(1, 1, At, B1); PG8_BAR; PG8_SCHED;
	s_add_i32 s28, s85, s44
	v_lshl_add_u64 v[224:225], v[224:225], 0, s[12:13]
	s_mov_b32 m0, s28
	ds_read_b128 v[160:163], v221 offset:49152
	ds_read_b128 v[164:167], v221 offset:50176
	ds_read_b128 v[168:171], v221 offset:51200
	ds_read_b128 v[172:175], v221 offset:52224
	ds_read_b128 v[176:179], v221 offset:53248
	ds_read_b128 v[180:183], v221 offset:54272
	ds_read_b128 v[184:187], v221 offset:55296
	ds_read_b128 v[188:191], v221 offset:56320
	global_load_lds_dwordx4 v[224:225], off
	s_add_i32 m0, s28, 0x2000
	s_add_u32 s26, s26, 0x40080
	v_lshl_add_u64 v[224:225], v[226:227], 0, s[12:13]
	s_addc_u32 s27, s27, 0
	s_add_i32 s28, s86, s44
	global_load_lds_dwordx4 v[224:225], off
	v_lshl_add_u64 v[224:225], s[26:27], 0, v[200:201]
	s_mov_b32 m0, s28
	s_nop 0
	global_load_lds_dwordx4 v[224:225], off
	v_lshl_add_u64 v[224:225], s[26:27], 0, v[196:197]
	s_add_i32 m0, s28, 0x2000
	s_nop 0
	global_load_lds_dwordx4 v[224:225], off
	v_lshl_add_u64 v[224:225], v[228:229], 0, s[12:13]
	s_mov_b32 m0, s62
	s_nop 0
	global_load_lds_dwordx4 v[224:225], off
	v_lshl_add_u64 v[224:225], v[230:231], 0, s[12:13]
	s_mov_b32 m0, s63
	s_nop 0
	global_load_lds_dwordx4 v[224:225], off
	s_waitcnt vmcnt(8)
	s_waitcnt lgkmcnt(0)
	s_barrier
	s_setprio 1
	s_waitcnt lgkmcnt(0)
	v_mfma_f32_16x16x32_bf16 v[60:63], v[128:131], v[160:163], v[60:63]
	v_mfma_f32_16x16x32_bf16 v[56:59], v[136:139], v[160:163], v[56:59]
	v_mfma_f32_16x16x32_bf16 v[52:55], v[128:131], v[168:171], v[52:55]
	v_mfma_f32_16x16x32_bf16 v[44:47], v[136:139], v[168:171], v[44:47]
	v_mfma_f32_16x16x32_bf16 v[36:39], v[128:131], v[176:179], v[36:39]
	v_mfma_f32_16x16x32_bf16 v[28:31], v[136:139], v[176:179], v[28:31]
	v_mfma_f32_16x16x32_bf16 v[20:23], v[128:131], v[184:187], v[20:23]
	v_mfma_f32_16x16x32_bf16 v[12:15], v[136:139], v[184:187], v[12:15]
	v_mfma_f32_16x16x32_bf16 v[60:63], v[132:135], v[164:167], v[60:63]
	v_mfma_f32_16x16x32_bf16 v[56:59], v[140:143], v[164:167], v[56:59]
	v_mfma_f32_16x16x32_bf16 v[52:55], v[132:135], v[172:175], v[52:55]
	v_mfma_f32_16x16x32_bf16 v[44:47], v[140:143], v[172:175], v[44:47]
	v_mfma_f32_16x16x32_bf16 v[36:39], v[132:135], v[180:183], v[36:39]
	v_mfma_f32_16x16x32_bf16 v[28:31], v[140:143], v[180:183], v[28:31]
	v_mfma_f32_16x16x32_bf16 v[20:23], v[132:135], v[188:191], v[20:23]
	v_mfma_f32_16x16x32_bf16 v[12:15], v[140:143], v[188:191], v[12:15]
	s_setprio 0
	s_setprio 1
	v_mfma_f32_16x16x32_bf16 v[48:51], v[144:147], v[160:163], v[48:51]
	v_mfma_f32_16x16x32_bf16 v[40:43], v[152:155], v[160:163], v[40:43]
	v_mfma_f32_16x16x32_bf16 v[32:35], v[144:147], v[168:171], v[32:35]
	v_mfma_f32_16x16x32_bf16 v[24:27], v[152:155], v[168:171], v[24:27]
	v_mfma_f32_16x16x32_bf16 v[16:19], v[144:147], v[176:179], v[16:19]
	v_mfma_f32_16x16x32_bf16 v[8:11], v[152:155], v[176:179], v[8:11]
	v_mfma_f32_16x16x32_bf16 v[4:7], v[144:147], v[184:187], v[4:7]
	v_mfma_f32_16x16x32_bf16 v[0:3], v[152:155], v[184:187], v[0:3]
	v_mfma_f32_16x16x32_bf16 v[48:51], v[148:151], v[164:167], v[48:51]
	v_mfma_f32_16x16x32_bf16 v[40:43], v[156:159], v[164:167], v[40:43]
	v_mfma_f32_16x16x32_bf16 v[32:35], v[148:151], v[172:175], v[32:35]
	v_mfma_f32_16x16x32_bf16 v[24:27], v[156:159], v[172:175], v[24:27]
	v_mfma_f32_16x16x32_bf16 v[16:19], v[148:151], v[180:183], v[16:19]
	v_mfma_f32_16x16x32_bf16 v[8:11], v[156:159], v[180:183], v[8:11]
	v_mfma_f32_16x16x32_bf16 v[4:7], v[148:151], v[188:191], v[4:7]
	v_mfma_f32_16x16x32_bf16 v[0:3], v[156:159], v[188:191], v[0:3]
	s_setprio 0
	s_barrier
	s_add_i32 s84, s84, 2
	s_add_u32 s24, s24, 0x100
	s_addc_u32 s25, s25, 0
	s_add_u32 s82, s82, 0x100
	s_addc_u32 s83, s83, 0

; #define PG8_STAGE(bufoff, gbase, voff) do { _Pragma("unroll") for (int _i = 0; _i < 2; ++_i) \
;         __builtin_amdgcn_global_load_lds((const unsigned*)((const char*)(gbase) + (voff)[_i]), (PG8_LAS unsigned*)(lds + (bufoff) + ldsw + _i * 8192), 16, 0, 0); } while (0)
; #define PG8_LDA(dst, b, h) do { _Pragma("unroll") for (int m = 0; m < 4; ++m) _Pragma("unroll") for (int k = 0; k < 2; ++k) dst[m][k] = *(const PG8_LAS bf16x8*)(lds + PG8_SA(b, h) + aoff + m * 2048 + k * 1024); } while (0)
; #define PG8_LDB(dst, b, h) do { _Pragma("unroll") for (int n = 0; n < 2; ++n) _Pragma("unroll") for (int k = 0; k < 2; ++k) dst[n][k] = *(const PG8_LAS bf16x8*)(lds + PG8_SB(b, h) + boff + n * 2048 + k * 1024); } while (0)
; #define PG8_WAIT_V(n) asm volatile("s_waitcnt vmcnt(" #n ")" ::: "memory")
; #define PG8_WAIT_L(n) asm volatile("s_waitcnt lgkmcnt(" #n ")" ::: "memory")
; #define PG8_BAR __builtin_amdgcn_s_barrier()
; #define PG8_SCHED __builtin_amdgcn_sched_barrier(0)
; template <class Epi, class Sched, bool ALIGN_EPI = false, bool SP2 = false>
; __device__ __forceinline__ void gemm_phase(PG8_LAS unsigned char* lds, const Gemm g, const Sched& S, const Epi& E) {
;     ...
;         const bool has_next = S.next(ui + 1, nxt);
;         const char* nA = has_next ? PG8_UA(nxt) : cA; const char* nB = has_next ? PG8_UB(nxt) : cB;
;         for (int t = 0; t < nt; t += 2) {
;             const bool last = (t == nt - 2);
;             const char* a1 = cA + (size_t)(t + 1) * kstep;
;             const char* a2 = last ? nA : cA + (size_t)(t + 2) * kstep; const char* b2 = last ? nB : cB + (size_t)(t + 2) * kstep;
;             const char* a3 = a2 + kstep; const char* b3 = b2 + kstep;
;             if (last && has_next) S.a_ready(nxt);
;             if constexpr (SP2) {
;             PG8_LDB(B0, 0, 0); PG8_LDB(B1, 0, 1); PG8_SCHED; PG8_LDA(At, 0, 0); PG8_STAGE(PG8_SA(1, 1), a1 + hstepA, voffA);
;             PG8_WAIT_V(8); PG8_WAIT_L(0); PG8_BAR; PG8_MMA(0, 0, At, B0); PG8_MMA(0, 1, At, B1); PG8_BAR; PG8_SCHED;
;             PG8_LDA(At, 0, 1); PG8_STAGE(PG8_SB(0, 0), b2, voffB); PG8_STAGE(PG8_SB(0, 1), b2 + hstepB, voffB); PG8_STAGE(PG8_SA(0, 0), a2, voffA);
;             PG8_WAIT_V(8); PG8_WAIT_L(0); PG8_BAR; PG8_MMA(1, 0, At, B0); PG8_MMA(1, 1, At, B1); PG8_BAR; PG8_SCHED;
.LBB0_1048:
	s_ashr_i32 s19, s18, 31
	s_lshl_b64 s[2:3], s[18:19], 19
	s_add_u32 s20, s30, s2
	s_addc_u32 s21, s31, s3
	s_and_b64 s[2:3], s[4:5], exec
	s_cselect_b32 s1, s21, s25
	s_cselect_b32 s2, s20, s24
	s_ashr_i32 s3, s18, 30
	s_add_i32 s22, s3, s55
	s_ashr_i32 s23, s22, 31
	s_lshl_b64 s[22:23], s[22:23], 19
	s_add_u32 s22, s33, s22
	s_addc_u32 s23, s36, s23
	s_and_b64 s[28:29], s[4:5], exec
	s_cselect_b32 s3, s23, s27
	s_cselect_b32 s19, s22, s26
	s_add_u32 s24, s24, 0x40080
	s_addc_u32 s25, s25, 0
	s_add_u32 s57, s26, 0x100
	s_addc_u32 s58, s27, 0
	s_mov_b32 s59, -2
	ds_read_b128 v[154:157], v149
	ds_read_b128 v[158:161], v149 offset:1024
	ds_read_b128 v[162:165], v149 offset:2048
	ds_read_b128 v[166:169], v149 offset:3072
	ds_read_b128 v[170:173], v150
	ds_read_b128 v[174:177], v150 offset:1024
	ds_read_b128 v[178:181], v150 offset:2048
	ds_read_b128 v[182:185], v150 offset:3072
	s_add_u32 s26, s24, 0xfffc0080
	s_addc_u32 s27, s25, -1
	s_cmp_eq_u32 s59, 12
	s_cselect_b32 s29, s1, s27
	s_cselect_b32 s28, s2, s26
	s_cselect_b32 s27, s3, s58
	s_cselect_b32 s26, s19, s57
	v_lshl_add_u64 v[144:145], s[24:25], 0, v[136:137]
	s_add_i32 m0, s42, 0xc000
	ds_read_b128 v[186:189], v151
	ds_read_b128 v[196:199], v151 offset:1024
	ds_read_b128 v[200:203], v151 offset:2048
	ds_read_b128 v[204:207], v151 offset:3072
	ds_read_b128 v[208:211], v151 offset:4096
	ds_read_b128 v[212:215], v151 offset:5120
	ds_read_b128 v[216:219], v151 offset:6144
	ds_read_b128 v[220:223], v151 offset:7168
	global_load_lds_dwordx4 v[144:145], off
	v_lshl_add_u64 v[144:145], s[24:25], 0, v[138:139]
	s_add_i32 m0, s42, 0xe000
	s_nop 0
	global_load_lds_dwordx4 v[144:145], off
	s_waitcnt vmcnt(8)
	s_waitcnt lgkmcnt(0)
	s_barrier
	s_setprio 1
	s_waitcnt lgkmcnt(0)
	v_mfma_f32_16x16x32_bf16 v[124:127], v[154:157], v[186:189], 0
	v_mfma_f32_16x16x32_bf16 v[120:123], v[162:165], v[186:189], 0
	v_mfma_f32_16x16x32_bf16 v[108:111], v[154:157], v[200:203], 0
	v_mfma_f32_16x16x32_bf16 v[104:107], v[162:165], v[200:203], 0
	v_mfma_f32_16x16x32_bf16 v[92:95], v[154:157], v[208:211], 0
	v_mfma_f32_16x16x32_bf16 v[88:91], v[162:165], v[208:211], 0
	v_mfma_f32_16x16x32_bf16 v[76:79], v[154:157], v[216:219], 0
	v_mfma_f32_16x16x32_bf16 v[72:75], v[162:165], v[216:219], 0
	v_mfma_f32_16x16x32_bf16 v[124:127], v[158:161], v[196:199], v[124:127]
	v_mfma_f32_16x16x32_bf16 v[120:123], v[166:169], v[196:199], v[120:123]
	v_mfma_f32_16x16x32_bf16 v[108:111], v[158:161], v[204:207], v[108:111]
	v_mfma_f32_16x16x32_bf16 v[104:107], v[166:169], v[204:207], v[104:107]
	v_mfma_f32_16x16x32_bf16 v[92:95], v[158:161], v[212:215], v[92:95]
	v_mfma_f32_16x16x32_bf16 v[88:91], v[166:169], v[212:215], v[88:91]
	v_mfma_f32_16x16x32_bf16 v[76:79], v[158:161], v[220:223], v[76:79]
	v_mfma_f32_16x16x32_bf16 v[72:75], v[166:169], v[220:223], v[72:75]
	s_setprio 0
	s_setprio 1
	v_mfma_f32_16x16x32_bf16 v[116:119], v[170:173], v[186:189], 0
	v_mfma_f32_16x16x32_bf16 v[112:115], v[178:181], v[186:189], 0
	v_mfma_f32_16x16x32_bf16 v[100:103], v[170:173], v[200:203], 0
	v_mfma_f32_16x16x32_bf16 v[96:99], v[178:181], v[200:203], 0
	v_mfma_f32_16x16x32_bf16 v[84:87], v[170:173], v[208:211], 0
	v_mfma_f32_16x16x32_bf16 v[80:83], v[178:181], v[208:211], 0
	v_mfma_f32_16x16x32_bf16 v[68:71], v[170:173], v[216:219], 0
	v_mfma_f32_16x16x32_bf16 v[64:67], v[178:181], v[216:219], 0
	v_mfma_f32_16x16x32_bf16 v[116:119], v[174:177], v[196:199], v[116:119]
	v_mfma_f32_16x16x32_bf16 v[112:115], v[182:185], v[196:199], v[112:115]
	v_mfma_f32_16x16x32_bf16 v[100:103], v[174:177], v[204:207], v[100:103]
	v_mfma_f32_16x16x32_bf16 v[96:99], v[182:185], v[204:207], v[96:99]
	v_mfma_f32_16x16x32_bf16 v[84:87], v[174:177], v[212:215], v[84:87]
	v_mfma_f32_16x16x32_bf16 v[80:83], v[182:185], v[212:215], v[80:83]
	v_mfma_f32_16x16x32_bf16 v[68:71], v[174:177], v[220:223], v[68:71]
	v_mfma_f32_16x16x32_bf16 v[64:67], v[182:185], v[220:223], v[64:67]
	s_setprio 0
	s_barrier
	s_add_i32 s60, s51, s37
	v_lshl_add_u64 v[144:145], s[26:27], 0, v[132:133]
	s_mov_b32 m0, s60
	ds_read_b128 v[186:189], v151 offset:16384
	ds_read_b128 v[196:199], v151 offset:17408
	ds_read_b128 v[200:203], v151 offset:18432
	ds_read_b128 v[204:207], v151 offset:19456
	ds_read_b128 v[208:211], v151 offset:20480
	ds_read_b128 v[212:215], v151 offset:21504
	ds_read_b128 v[216:219], v151 offset:22528
	ds_read_b128 v[220:223], v151 offset:23552
	global_load_lds_dwordx4 v[144:145], off
	s_add_i32 m0, s60, 0x2000
	s_add_u32 s60, s26, 0x40000
	v_lshl_add_u64 v[190:191], s[26:27], 0, v[128:129]
	s_addc_u32 s61, s27, 0
	s_add_i32 s62, s52, s37
	global_load_lds_dwordx4 v[190:191], off
	v_lshl_add_u64 v[224:225], s[60:61], 0, v[132:133]
	s_mov_b32 m0, s62
	v_lshl_add_u64 v[226:227], s[28:29], 0, v[130:131]
	global_load_lds_dwordx4 v[224:225], off
	v_lshl_add_u64 v[224:225], s[60:61], 0, v[128:129]
	s_add_i32 m0, s62, 0x2000
	s_nop 0
	global_load_lds_dwordx4 v[224:225], off
	v_lshl_add_u64 v[224:225], s[28:29], 0, v[134:135]
	s_mov_b32 m0, s42
	s_nop 0
	global_load_lds_dwordx4 v[224:225], off
	s_mov_b32 m0, s43
	s_nop 0
	global_load_lds_dwordx4 v[226:227], off
	s_waitcnt vmcnt(8)
	s_waitcnt lgkmcnt(0)
	s_barrier
; #define PG8_STAGE(bufoff, gbase, voff) do { _Pragma("unroll") for (int _i = 0; _i < 2; ++_i) \
;         __builtin_amdgcn_global_load_lds((const unsigned*)((const char*)(gbase) + (voff)[_i]), (PG8_LAS unsigned*)(lds + (bufoff) + ldsw + _i * 8192), 16, 0, 0); } while (0)
; #define PG8_LDA(dst, b, h) do { _Pragma("unroll") for (int m = 0; m < 4; ++m) _Pragma("unroll") for (int k = 0; k < 2; ++k) dst[m][k] = *(const PG8_LAS bf16x8*)(lds + PG8_SA(b, h) + aoff + m * 2048 + k * 1024); } while (0)
; #define PG8_LDB(dst, b, h) do { _Pragma("unroll") for (int n = 0; n < 2; ++n) _Pragma("unroll") for (int k = 0; k < 2; ++k) dst[n][k] = *(const PG8_LAS bf16x8*)(lds + PG8_SB(b, h) + boff + n * 2048 + k * 1024); } while (0)
; #define PG8_MMA(ai, bj, At, Bt) do { __builtin_amdgcn_s_setprio(1); _Pragma("unroll") for (int m = 0; m < 4; ++m) _Pragma("unroll") for (int n = 0; n < 2; ++n) _Pragma("unroll") for (int k = 0; k < 2; ++k) \
;         acc[ai][bj][m][n] = __builtin_amdgcn_mfma_f32_16x16x32_bf16(Bt[n][k], At[m][k], acc[ai][bj][m][n], 0, 0, 0); __builtin_amdgcn_s_setprio(0); } while (0)
; #define PG8_WAIT_V(n) asm volatile("s_waitcnt vmcnt(" #n ")" ::: "memory")
; #define PG8_WAIT_L(n) asm volatile("s_waitcnt lgkmcnt(" #n ")" ::: "memory")
; #define PG8_BAR __builtin_amdgcn_s_barrier()
; #define PG8_SCHED __builtin_amdgcn_sched_barrier(0)
; template <class Epi, class Sched, bool ALIGN_EPI = false, bool SP2 = false>
; __device__ __forceinline__ void gemm_phase(PG8_LAS unsigned char* lds, const Gemm g, const Sched& S, const Epi& E) {
;     ...
;             PG8_WAIT_V(8); PG8_WAIT_L(0); PG8_BAR; PG8_MMA(1, 0, At, B0); PG8_MMA(1, 1, At, B1); PG8_BAR; PG8_SCHED;
;             PG8_LDB(B0, 1, 0); PG8_LDB(B1, 1, 1); PG8_SCHED; PG8_LDA(At, 1, 0); PG8_STAGE(PG8_SA(0, 1), a2 + hstepA, voffA);
;             PG8_WAIT_V(8); PG8_WAIT_L(0); PG8_BAR; PG8_MMA(0, 0, At, B0); PG8_MMA(0, 1, At, B1); PG8_BAR; PG8_SCHED;
	s_setprio 1
	s_waitcnt lgkmcnt(0)
	v_mfma_f32_16x16x32_bf16 v[60:63], v[154:157], v[186:189], 0
	v_mfma_f32_16x16x32_bf16 v[56:59], v[162:165], v[186:189], 0
	v_mfma_f32_16x16x32_bf16 v[44:47], v[154:157], v[200:203], 0
	v_mfma_f32_16x16x32_bf16 v[40:43], v[162:165], v[200:203], 0
	v_mfma_f32_16x16x32_bf16 v[28:31], v[154:157], v[208:211], 0
	v_mfma_f32_16x16x32_bf16 v[24:27], v[162:165], v[208:211], 0
	v_mfma_f32_16x16x32_bf16 v[12:15], v[154:157], v[216:219], 0
	v_mfma_f32_16x16x32_bf16 v[8:11], v[162:165], v[216:219], 0
	v_mfma_f32_16x16x32_bf16 v[60:63], v[158:161], v[196:199], v[60:63]
	v_mfma_f32_16x16x32_bf16 v[56:59], v[166:169], v[196:199], v[56:59]
	v_mfma_f32_16x16x32_bf16 v[44:47], v[158:161], v[204:207], v[44:47]
	v_mfma_f32_16x16x32_bf16 v[40:43], v[166:169], v[204:207], v[40:43]
	v_mfma_f32_16x16x32_bf16 v[28:31], v[158:161], v[212:215], v[28:31]
	v_mfma_f32_16x16x32_bf16 v[24:27], v[166:169], v[212:215], v[24:27]
	v_mfma_f32_16x16x32_bf16 v[12:15], v[158:161], v[220:223], v[12:15]
	v_mfma_f32_16x16x32_bf16 v[8:11], v[166:169], v[220:223], v[8:11]
	s_setprio 0
	s_setprio 1
	v_mfma_f32_16x16x32_bf16 v[52:55], v[170:173], v[186:189], 0
	v_mfma_f32_16x16x32_bf16 v[48:51], v[178:181], v[186:189], 0
	v_mfma_f32_16x16x32_bf16 v[36:39], v[170:173], v[200:203], 0
	v_mfma_f32_16x16x32_bf16 v[32:35], v[178:181], v[200:203], 0
	v_mfma_f32_16x16x32_bf16 v[20:23], v[170:173], v[208:211], 0
	v_mfma_f32_16x16x32_bf16 v[16:19], v[178:181], v[208:211], 0
	v_mfma_f32_16x16x32_bf16 v[4:7], v[170:173], v[216:219], 0
	v_mfma_f32_16x16x32_bf16 v[0:3], v[178:181], v[216:219], 0
	v_mfma_f32_16x16x32_bf16 v[52:55], v[174:177], v[196:199], v[52:55]
	v_mfma_f32_16x16x32_bf16 v[48:51], v[182:185], v[196:199], v[48:51]
	v_mfma_f32_16x16x32_bf16 v[36:39], v[174:177], v[204:207], v[36:39]
	v_mfma_f32_16x16x32_bf16 v[32:35], v[182:185], v[204:207], v[32:35]
	v_mfma_f32_16x16x32_bf16 v[20:23], v[174:177], v[212:215], v[20:23]
	v_mfma_f32_16x16x32_bf16 v[16:19], v[182:185], v[212:215], v[16:19]
	v_mfma_f32_16x16x32_bf16 v[4:7], v[174:177], v[220:223], v[4:7]
	v_mfma_f32_16x16x32_bf16 v[0:3], v[182:185], v[220:223], v[0:3]
	s_setprio 0
	s_barrier
	s_add_i32 s60, 0, 0x18000
	s_add_i32 s61, 0, 0x1c000
	v_add_u32_e32 v166, s60, v147
	v_add_u32_e32 v182, s61, v147
	ds_read_b128 v[154:157], v166
	ds_read_b128 v[158:161], v166 offset:1024
	ds_read_b128 v[162:165], v166 offset:2048
	ds_read_b128 v[166:169], v166 offset:3072
	ds_read_b128 v[170:173], v182
	ds_read_b128 v[174:177], v182 offset:1024
	ds_read_b128 v[178:181], v182 offset:2048
	ds_read_b128 v[182:185], v182 offset:3072
	s_add_u32 s28, s28, 0x40000
	s_addc_u32 s29, s29, 0
	s_mov_b32 m0, s44
	v_lshl_add_u64 v[228:229], s[28:29], 0, v[134:135]
	ds_read_b128 v[186:189], v151 offset:32768
	ds_read_b128 v[196:199], v151 offset:33792
	ds_read_b128 v[200:203], v151 offset:34816
	ds_read_b128 v[204:207], v151 offset:35840
	ds_read_b128 v[208:211], v151 offset:36864
	ds_read_b128 v[212:215], v151 offset:37888
	ds_read_b128 v[216:219], v151 offset:38912
	ds_read_b128 v[220:223], v151 offset:39936
	global_load_lds_dwordx4 v[228:229], off
	v_lshl_add_u64 v[228:229], s[28:29], 0, v[130:131]
	s_mov_b32 m0, s45
	s_nop 0
	global_load_lds_dwordx4 v[228:229], off
	s_waitcnt vmcnt(8)
	s_waitcnt lgkmcnt(0)
	s_barrier
	s_setprio 1
	s_waitcnt lgkmcnt(0)
	v_mfma_f32_16x16x32_bf16 v[124:127], v[154:157], v[186:189], v[124:127]
	v_mfma_f32_16x16x32_bf16 v[120:123], v[162:165], v[186:189], v[120:123]
	v_mfma_f32_16x16x32_bf16 v[108:111], v[154:157], v[200:203], v[108:111]
	v_mfma_f32_16x16x32_bf16 v[104:107], v[162:165], v[200:203], v[104:107]
	v_mfma_f32_16x16x32_bf16 v[92:95], v[154:157], v[208:211], v[92:95]
	v_mfma_f32_16x16x32_bf16 v[88:91], v[162:165], v[208:211], v[88:91]
	v_mfma_f32_16x16x32_bf16 v[76:79], v[154:157], v[216:219], v[76:79]
	v_mfma_f32_16x16x32_bf16 v[72:75], v[162:165], v[216:219], v[72:75]
	v_mfma_f32_16x16x32_bf16 v[124:127], v[158:161], v[196:199], v[124:127]
	v_mfma_f32_16x16x32_bf16 v[120:123], v[166:169], v[196:199], v[120:123]
	v_mfma_f32_16x16x32_bf16 v[108:111], v[158:161], v[204:207], v[108:111]
	v_mfma_f32_16x16x32_bf16 v[104:107], v[166:169], v[204:207], v[104:107]
	v_mfma_f32_16x16x32_bf16 v[92:95], v[158:161], v[212:215], v[92:95]
	v_mfma_f32_16x16x32_bf16 v[88:91], v[166:169], v[212:215], v[88:91]
	v_mfma_f32_16x16x32_bf16 v[76:79], v[158:161], v[220:223], v[76:79]
	v_mfma_f32_16x16x32_bf16 v[72:75], v[166:169], v[220:223], v[72:75]
	s_setprio 0
	s_setprio 1
	v_mfma_f32_16x16x32_bf16 v[116:119], v[170:173], v[186:189], v[116:119]
	v_mfma_f32_16x16x32_bf16 v[112:115], v[178:181], v[186:189], v[112:115]
	v_mfma_f32_16x16x32_bf16 v[100:103], v[170:173], v[200:203], v[100:103]
	v_mfma_f32_16x16x32_bf16 v[96:99], v[178:181], v[200:203], v[96:99]
	v_mfma_f32_16x16x32_bf16 v[84:87], v[170:173], v[208:211], v[84:87]
	v_mfma_f32_16x16x32_bf16 v[80:83], v[178:181], v[208:211], v[80:83]
	v_mfma_f32_16x16x32_bf16 v[68:71], v[170:173], v[216:219], v[68:71]
	v_mfma_f32_16x16x32_bf16 v[64:67], v[178:181], v[216:219], v[64:67]
	v_mfma_f32_16x16x32_bf16 v[116:119], v[174:177], v[196:199], v[116:119]
	v_mfma_f32_16x16x32_bf16 v[112:115], v[182:185], v[196:199], v[112:115]
	v_mfma_f32_16x16x32_bf16 v[100:103], v[174:177], v[204:207], v[100:103]
	v_mfma_f32_16x16x32_bf16 v[96:99], v[182:185], v[204:207], v[96:99]
	v_mfma_f32_16x16x32_bf16 v[84:87], v[174:177], v[212:215], v[84:87]
	v_mfma_f32_16x16x32_bf16 v[80:83], v[182:185], v[212:215], v[80:83]
	v_mfma_f32_16x16x32_bf16 v[68:71], v[174:177], v[220:223], v[68:71]
	v_mfma_f32_16x16x32_bf16 v[64:67], v[182:185], v[220:223], v[64:67]
	s_setprio 0
	s_barrier
; #define PG8_STAGE(bufoff, gbase, voff) do { _Pragma("unroll") for (int _i = 0; _i < 2; ++_i) \
;         __builtin_amdgcn_global_load_lds((const unsigned*)((const char*)(gbase) + (voff)[_i]), (PG8_LAS unsigned*)(lds + (bufoff) + ldsw + _i * 8192), 16, 0, 0); } while (0)
; #define PG8_LDA(dst, b, h) do { _Pragma("unroll") for (int m = 0; m < 4; ++m) _Pragma("unroll") for (int k = 0; k < 2; ++k) dst[m][k] = *(const PG8_LAS bf16x8*)(lds + PG8_SA(b, h) + aoff + m * 2048 + k * 1024); } while (0)
; #define PG8_MMA(ai, bj, At, Bt) do { __builtin_amdgcn_s_setprio(1); _Pragma("unroll") for (int m = 0; m < 4; ++m) _Pragma("unroll") for (int n = 0; n < 2; ++n) _Pragma("unroll") for (int k = 0; k < 2; ++k) \
;         acc[ai][bj][m][n] = __builtin_amdgcn_mfma_f32_16x16x32_bf16(Bt[n][k], At[m][k], acc[ai][bj][m][n], 0, 0, 0); __builtin_amdgcn_s_setprio(0); } while (0)
; #define PG8_WAIT_V(n) asm volatile("s_waitcnt vmcnt(" #n ")" ::: "memory")
; #define PG8_WAIT_L(n) asm volatile("s_waitcnt lgkmcnt(" #n ")" ::: "memory")
; #define PG8_BAR __builtin_amdgcn_s_barrier()
; #define PG8_SCHED __builtin_amdgcn_sched_barrier(0)
; template <class Epi, class Sched, bool ALIGN_EPI = false, bool SP2 = false>
; __device__ __forceinline__ void gemm_phase(PG8_LAS unsigned char* lds, const Gemm g, const Sched& S, const Epi& E) {
;     ...
;             PG8_LDA(At, 1, 1); PG8_STAGE(PG8_SB(1, 0), b3, voffB); PG8_STAGE(PG8_SB(1, 1), b3 + hstepB, voffB); PG8_STAGE(PG8_SA(1, 0), a3, voffA);
;             PG8_WAIT_V(8); PG8_WAIT_L(0); PG8_BAR; PG8_MMA(1, 0, At, B0); PG8_MMA(1, 1, At, B1); PG8_BAR; PG8_SCHED;
	s_add_i32 s28, s60, s37
	v_lshl_add_u64 v[144:145], v[144:145], 0, s[14:15]
	s_mov_b32 m0, s28
	ds_read_b128 v[186:189], v151 offset:49152
	ds_read_b128 v[196:199], v151 offset:50176
	ds_read_b128 v[200:203], v151 offset:51200
	ds_read_b128 v[204:207], v151 offset:52224
	ds_read_b128 v[208:211], v151 offset:53248
	ds_read_b128 v[212:215], v151 offset:54272
	ds_read_b128 v[216:219], v151 offset:55296
	ds_read_b128 v[220:223], v151 offset:56320
	global_load_lds_dwordx4 v[144:145], off
	s_add_i32 m0, s28, 0x2000
	s_add_u32 s26, s26, 0x40080
	v_lshl_add_u64 v[144:145], v[190:191], 0, s[14:15]
	s_addc_u32 s27, s27, 0
	s_add_i32 s28, s61, s37
	global_load_lds_dwordx4 v[144:145], off
	v_lshl_add_u64 v[144:145], s[26:27], 0, v[132:133]
	s_mov_b32 m0, s28
	s_nop 0
	global_load_lds_dwordx4 v[144:145], off
	v_lshl_add_u64 v[144:145], s[26:27], 0, v[128:129]
	s_add_i32 m0, s28, 0x2000
	s_nop 0
	global_load_lds_dwordx4 v[144:145], off
	v_lshl_add_u64 v[144:145], v[224:225], 0, s[14:15]
	s_mov_b32 m0, s47
	s_nop 0
	global_load_lds_dwordx4 v[144:145], off
	v_lshl_add_u64 v[144:145], v[226:227], 0, s[14:15]
	s_mov_b32 m0, s48
	s_nop 0
	global_load_lds_dwordx4 v[144:145], off
	s_waitcnt vmcnt(8)
	s_waitcnt lgkmcnt(0)
	s_barrier
	s_setprio 1
	s_waitcnt lgkmcnt(0)
	v_mfma_f32_16x16x32_bf16 v[60:63], v[154:157], v[186:189], v[60:63]
	v_mfma_f32_16x16x32_bf16 v[56:59], v[162:165], v[186:189], v[56:59]
	v_mfma_f32_16x16x32_bf16 v[44:47], v[154:157], v[200:203], v[44:47]
	v_mfma_f32_16x16x32_bf16 v[40:43], v[162:165], v[200:203], v[40:43]
	v_mfma_f32_16x16x32_bf16 v[28:31], v[154:157], v[208:211], v[28:31]
	v_mfma_f32_16x16x32_bf16 v[24:27], v[162:165], v[208:211], v[24:27]
	v_mfma_f32_16x16x32_bf16 v[12:15], v[154:157], v[216:219], v[12:15]
	v_mfma_f32_16x16x32_bf16 v[8:11], v[162:165], v[216:219], v[8:11]
	v_mfma_f32_16x16x32_bf16 v[60:63], v[158:161], v[196:199], v[60:63]
	v_mfma_f32_16x16x32_bf16 v[56:59], v[166:169], v[196:199], v[56:59]
	v_mfma_f32_16x16x32_bf16 v[44:47], v[158:161], v[204:207], v[44:47]
	v_mfma_f32_16x16x32_bf16 v[40:43], v[166:169], v[204:207], v[40:43]
	v_mfma_f32_16x16x32_bf16 v[28:31], v[158:161], v[212:215], v[28:31]
	v_mfma_f32_16x16x32_bf16 v[24:27], v[166:169], v[212:215], v[24:27]
	v_mfma_f32_16x16x32_bf16 v[12:15], v[158:161], v[220:223], v[12:15]
	v_mfma_f32_16x16x32_bf16 v[8:11], v[166:169], v[220:223], v[8:11]
	s_setprio 0
	s_setprio 1
	v_mfma_f32_16x16x32_bf16 v[52:55], v[170:173], v[186:189], v[52:55]
	v_mfma_f32_16x16x32_bf16 v[48:51], v[178:181], v[186:189], v[48:51]
	v_mfma_f32_16x16x32_bf16 v[36:39], v[170:173], v[200:203], v[36:39]
	v_mfma_f32_16x16x32_bf16 v[32:35], v[178:181], v[200:203], v[32:35]
	v_mfma_f32_16x16x32_bf16 v[20:23], v[170:173], v[208:211], v[20:23]
	v_mfma_f32_16x16x32_bf16 v[16:19], v[178:181], v[208:211], v[16:19]
	v_mfma_f32_16x16x32_bf16 v[4:7], v[170:173], v[216:219], v[4:7]
	v_mfma_f32_16x16x32_bf16 v[0:3], v[178:181], v[216:219], v[0:3]
	v_mfma_f32_16x16x32_bf16 v[52:55], v[174:177], v[196:199], v[52:55]
	v_mfma_f32_16x16x32_bf16 v[48:51], v[182:185], v[196:199], v[48:51]
	v_mfma_f32_16x16x32_bf16 v[36:39], v[174:177], v[204:207], v[36:39]
	v_mfma_f32_16x16x32_bf16 v[32:35], v[182:185], v[204:207], v[32:35]
	v_mfma_f32_16x16x32_bf16 v[20:23], v[174:177], v[212:215], v[20:23]
	v_mfma_f32_16x16x32_bf16 v[16:19], v[182:185], v[212:215], v[16:19]
	v_mfma_f32_16x16x32_bf16 v[4:7], v[174:177], v[220:223], v[4:7]
	v_mfma_f32_16x16x32_bf16 v[0:3], v[182:185], v[220:223], v[0:3]
	s_setprio 0
	s_barrier
	s_add_i32 s59, s59, 2
	s_add_u32 s24, s24, 0x100
	s_addc_u32 s25, s25, 0
	s_add_u32 s57, s57, 0x100
	s_addc_u32 s58, s58, 0
